# c15: sigmoid/silu in-proj epilogue sequences use packed f32 add/mul (same operations, fewer VALU issues)
# speedup vs baseline: 1.0068x; 1.0068x over previous
; __device__ __forceinline__ float siluf(float v) { return v * __builtin_amdgcn_rcpf(1.f + __builtin_amdgcn_exp2f(-1.4426950408889634f * v)); }
; __device__ __forceinline__ float sigmf(float v) { return __builtin_amdgcn_rcpf(1.f + __builtin_amdgcn_exp2f(-1.4426950408889634f * v)); }
; #define G1_STG(mi_, ni_, v_) do { const int r_ = (mi_) * 16 + idx; const f32x4 t_ = (v_); u32x2 pk_; pk_.x = pk2(t_.x, t_.y); pk_.y = pk2(t_.z, t_.w); \
;         *(u32x2*)(wl + r_ * 128 + ((((ni_) * 2 + (kq >> 1)) ^ (r_ & 7)) * 16) + (kq & 1) * 8) = pk_; } while (0)
; __device__ void gemm1_phase(const Params& p, int l, int hb, unsigned char* smem) {
;     ...
;             int mode;
;             if (cw < 768) { dbase = (bf16_t*)(p.ws + WS_VA); dpitch = 128; dc0 = cw - 640; mode = 0; }
;             else if (cw < 1280) { dbase = (bf16_t*)(p.ws + WS_GA); dpitch = 512; dc0 = cw - 768; mode = 1; }
;             else if (cw < 3840) { dbase = (bf16_t*)(p.ws + WS_GB); dpitch = 256; dc0 = cw - 3584; mode = 1; }
;             else if (cw < 4864) { dbase = (bf16_t*)(p.ws + WS_XBC); dpitch = 1024; dc0 = cw - 3840; mode = 0; }
;             else if (cw < 5376) { dbase = (bf16_t*)(p.ws + WS_ZS); dpitch = 512; dc0 = cw - 4864; mode = 1; }
;             else { dbase = (bf16_t*)(p.ws + WS_MG); dpitch = 3072; dc0 = cw - 5376; mode = 2; }
;             const float* bg = p.b_gate + l * 3072 + dc0 + lc;
; #pragma unroll
;             for (int mi = 0; mi < 8; ++mi) {
; #pragma unroll
;                 for (int ni = 0; ni < 4; ++ni) {
;                     f32x4 v = acc[mi][ni];
;                     if (mode == 1) { v.x = siluf(v.x); v.y = siluf(v.y); v.z = siluf(v.z); v.w = siluf(v.w); }
;                     else if (mode == 2) { const f32x4 bb = *(const f32x4*)(bg + ni * 16); v.x = sigmf(v.x + bb.x); v.y = sigmf(v.y + bb.y); v.z = sigmf(v.z + bb.z); v.w = sigmf(v.w + bb.w); }
;                     G1_STG(mi, ni, v);
.LBB0_271:
	s_add_i32 s58, s9, s54
	s_ashr_i32 s59, s58, 31
	s_xor_b64 s[62:63], s[38:39], -1
	s_lshl_b64 s[16:17], s[58:59], 2
	s_add_u32 s16, s25, s16
	s_addc_u32 s17, s51, s17
	v_lshlrev_b32_e32 v80, 2, v157
	v_lshl_add_u64 v[130:131], s[16:17], 0, v[80:81]
	global_load_dwordx4 v[160:163], v[130:131], off
	global_load_dwordx4 v[164:167], v[130:131], off offset:64
	global_load_dwordx4 v[168:171], v[130:131], off offset:128
	global_load_dwordx4 v[172:175], v[130:131], off offset:192
	v_readlane_b32 s66, v255, 56
	v_readlane_b32 s67, v255, 57
	v_lshlrev_b32_e32 v130, 7, v231
	v_and_b32_e32 v131, 1, v156
	v_lshl_add_u32 v130, v131, 3, v130
	v_add_u32_e32 v130, s61, v130
	v_lshrrev_b32_e32 v131, 1, v156
	v_and_b32_e32 v132, 7, v231
	v_or_b32_e32 v133, 0, v131
	v_xor_b32_e32 v133, v133, v132
	v_lshl_add_u32 v136, v133, 4, v130
	v_or_b32_e32 v133, 2, v131
	v_xor_b32_e32 v133, v133, v132
	v_lshl_add_u32 v137, v133, 4, v130
	v_or_b32_e32 v133, 4, v131
	v_xor_b32_e32 v133, v133, v132
	v_lshl_add_u32 v138, v133, 4, v130
	v_or_b32_e32 v133, 6, v131
	v_xor_b32_e32 v133, v133, v132
	v_lshl_add_u32 v139, v133, 4, v130
	v_mov_b32_e32 v134, 0xbfb8aa3b
	v_mov_b32_e32 v135, 0xbfb8aa3b
	v_mov_b32_e32 v140, 1.0
	v_mov_b32_e32 v141, 1.0
	s_and_b64 vcc, exec, s[36:37]
	s_cbranch_vccnz .Lg1e_sig
	s_and_b64 vcc, exec, s[38:39]
	s_cbranch_vccnz .Lg1e_silu
	v_cvt_pk_bf16_f32 v126, v126, v127
	v_cvt_pk_bf16_f32 v127, v128, v129
	ds_write_b64 v136, v[126:127]
	v_cvt_pk_bf16_f32 v122, v122, v123
	v_cvt_pk_bf16_f32 v123, v124, v125
	ds_write_b64 v137, v[122:123]
	v_cvt_pk_bf16_f32 v118, v118, v119
	v_cvt_pk_bf16_f32 v119, v120, v121
	ds_write_b64 v138, v[118:119]
	v_cvt_pk_bf16_f32 v114, v114, v115
	v_cvt_pk_bf16_f32 v115, v116, v117
	ds_write_b64 v139, v[114:115]
	v_cvt_pk_bf16_f32 v110, v110, v111
	v_cvt_pk_bf16_f32 v111, v112, v113
	ds_write_b64 v136, v[110:111] offset:2048
	v_cvt_pk_bf16_f32 v106, v106, v107
	v_cvt_pk_bf16_f32 v107, v108, v109
	ds_write_b64 v137, v[106:107] offset:2048
	v_cvt_pk_bf16_f32 v102, v102, v103
	v_cvt_pk_bf16_f32 v103, v104, v105
	ds_write_b64 v138, v[102:103] offset:2048
	v_cvt_pk_bf16_f32 v98, v98, v99
	v_cvt_pk_bf16_f32 v99, v100, v101
	ds_write_b64 v139, v[98:99] offset:2048
	v_cvt_pk_bf16_f32 v94, v94, v95
	v_cvt_pk_bf16_f32 v95, v96, v97
	ds_write_b64 v136, v[94:95] offset:4096
	v_cvt_pk_bf16_f32 v90, v90, v91
	v_cvt_pk_bf16_f32 v91, v92, v93
	ds_write_b64 v137, v[90:91] offset:4096
	v_cvt_pk_bf16_f32 v86, v86, v87
	v_cvt_pk_bf16_f32 v87, v88, v89
	ds_write_b64 v138, v[86:87] offset:4096
	v_cvt_pk_bf16_f32 v82, v82, v83
	v_cvt_pk_bf16_f32 v83, v84, v85
	ds_write_b64 v139, v[82:83] offset:4096
	v_cvt_pk_bf16_f32 v76, v76, v77
	v_cvt_pk_bf16_f32 v77, v78, v79
	ds_write_b64 v136, v[76:77] offset:6144
	v_cvt_pk_bf16_f32 v72, v72, v73
	v_cvt_pk_bf16_f32 v73, v74, v75
	ds_write_b64 v137, v[72:73] offset:6144
	v_cvt_pk_bf16_f32 v68, v68, v69
	v_cvt_pk_bf16_f32 v69, v70, v71
	ds_write_b64 v138, v[68:69] offset:6144
	v_cvt_pk_bf16_f32 v64, v64, v65
	v_cvt_pk_bf16_f32 v65, v66, v67
	ds_write_b64 v139, v[64:65] offset:6144
	v_cvt_pk_bf16_f32 v60, v60, v61
	v_cvt_pk_bf16_f32 v61, v62, v63
	ds_write_b64 v136, v[60:61] offset:8192
	v_cvt_pk_bf16_f32 v56, v56, v57
	v_cvt_pk_bf16_f32 v57, v58, v59
	ds_write_b64 v137, v[56:57] offset:8192
	v_cvt_pk_bf16_f32 v52, v52, v53
	v_cvt_pk_bf16_f32 v53, v54, v55
	ds_write_b64 v138, v[52:53] offset:8192
	v_cvt_pk_bf16_f32 v48, v48, v49
	v_cvt_pk_bf16_f32 v49, v50, v51
	ds_write_b64 v139, v[48:49] offset:8192
	v_cvt_pk_bf16_f32 v44, v44, v45
	v_cvt_pk_bf16_f32 v45, v46, v47
	ds_write_b64 v136, v[44:45] offset:10240
	v_cvt_pk_bf16_f32 v40, v40, v41
	v_cvt_pk_bf16_f32 v41, v42, v43
	ds_write_b64 v137, v[40:41] offset:10240
	v_cvt_pk_bf16_f32 v36, v36, v37
	v_cvt_pk_bf16_f32 v37, v38, v39
	ds_write_b64 v138, v[36:37] offset:10240
	v_cvt_pk_bf16_f32 v32, v32, v33
	v_cvt_pk_bf16_f32 v33, v34, v35
	ds_write_b64 v139, v[32:33] offset:10240
	v_cvt_pk_bf16_f32 v28, v28, v29
	v_cvt_pk_bf16_f32 v29, v30, v31
	ds_write_b64 v136, v[28:29] offset:12288
	v_cvt_pk_bf16_f32 v24, v24, v25
	v_cvt_pk_bf16_f32 v25, v26, v27
	ds_write_b64 v137, v[24:25] offset:12288
	v_cvt_pk_bf16_f32 v20, v20, v21
	v_cvt_pk_bf16_f32 v21, v22, v23
	ds_write_b64 v138, v[20:21] offset:12288
	v_cvt_pk_bf16_f32 v16, v16, v17
	v_cvt_pk_bf16_f32 v17, v18, v19
	ds_write_b64 v139, v[16:17] offset:12288
	v_cvt_pk_bf16_f32 v12, v12, v13
	v_cvt_pk_bf16_f32 v13, v14, v15
	ds_write_b64 v136, v[12:13] offset:14336
	v_cvt_pk_bf16_f32 v8, v8, v9
	v_cvt_pk_bf16_f32 v9, v10, v11
	ds_write_b64 v137, v[8:9] offset:14336
	v_cvt_pk_bf16_f32 v4, v4, v5
	v_cvt_pk_bf16_f32 v5, v6, v7
	ds_write_b64 v138, v[4:5] offset:14336
	v_cvt_pk_bf16_f32 v0, v0, v1
	v_cvt_pk_bf16_f32 v1, v2, v3
	ds_write_b64 v139, v[0:1] offset:14336
	s_branch .Lg1e_done
; __device__ __forceinline__ float sigmf(float v) { return __builtin_amdgcn_rcpf(1.f + __builtin_amdgcn_exp2f(-1.4426950408889634f * v)); }
; #define G1_STG(mi_, ni_, v_) do { const int r_ = (mi_) * 16 + idx; const f32x4 t_ = (v_); u32x2 pk_; pk_.x = pk2(t_.x, t_.y); pk_.y = pk2(t_.z, t_.w); \
;         *(u32x2*)(wl + r_ * 128 + ((((ni_) * 2 + (kq >> 1)) ^ (r_ & 7)) * 16) + (kq & 1) * 8) = pk_; } while (0)
; __device__ __forceinline__ float siluf(float v) { return v * __builtin_amdgcn_rcpf(1.f + __builtin_amdgcn_exp2f(-1.4426950408889634f * v)); }
; __device__ void gemm1_phase(const Params& p, int l, int hb, unsigned char* smem) {
;     ...
;                 for (int ni = 0; ni < 4; ++ni) {
;                     f32x4 v = acc[mi][ni];
;                     if (mode == 1) { v.x = siluf(v.x); v.y = siluf(v.y); v.z = siluf(v.z); v.w = siluf(v.w); }
;                     else if (mode == 2) { const f32x4 bb = *(const f32x4*)(bg + ni * 16); v.x = sigmf(v.x + bb.x); v.y = sigmf(v.y + bb.y); v.z = sigmf(v.z + bb.z); v.w = sigmf(v.w + bb.w); }
;                     G1_STG(mi, ni, v);
.Lg1e_silu:
	v_pk_mul_f32 v[130:131], v[126:127], v[134:135]
	v_pk_mul_f32 v[132:133], v[128:129], v[134:135]
	v_exp_f32_e32 v130, v130
	v_exp_f32_e32 v131, v131
	v_exp_f32_e32 v132, v132
	v_exp_f32_e32 v133, v133
	v_pk_add_f32 v[130:131], v[130:131], v[140:141]
	v_pk_add_f32 v[132:133], v[132:133], v[140:141]
	v_rcp_f32_e32 v130, v130
	v_rcp_f32_e32 v131, v131
	v_rcp_f32_e32 v132, v132
	v_rcp_f32_e32 v133, v133
	v_pk_mul_f32 v[126:127], v[126:127], v[130:131]
	v_pk_mul_f32 v[128:129], v[128:129], v[132:133]
	v_cvt_pk_bf16_f32 v126, v126, v127
	v_cvt_pk_bf16_f32 v127, v128, v129
	ds_write_b64 v136, v[126:127]
	v_pk_mul_f32 v[130:131], v[122:123], v[134:135]
	v_pk_mul_f32 v[132:133], v[124:125], v[134:135]
	v_exp_f32_e32 v130, v130
	v_exp_f32_e32 v131, v131
	v_exp_f32_e32 v132, v132
	v_exp_f32_e32 v133, v133
	v_pk_add_f32 v[130:131], v[130:131], v[140:141]
	v_pk_add_f32 v[132:133], v[132:133], v[140:141]
	v_rcp_f32_e32 v130, v130
	v_rcp_f32_e32 v131, v131
	v_rcp_f32_e32 v132, v132
	v_rcp_f32_e32 v133, v133
	v_pk_mul_f32 v[122:123], v[122:123], v[130:131]
	v_pk_mul_f32 v[124:125], v[124:125], v[132:133]
	v_cvt_pk_bf16_f32 v122, v122, v123
	v_cvt_pk_bf16_f32 v123, v124, v125
	ds_write_b64 v137, v[122:123]
	v_pk_mul_f32 v[130:131], v[118:119], v[134:135]
	v_pk_mul_f32 v[132:133], v[120:121], v[134:135]
	v_exp_f32_e32 v130, v130
	v_exp_f32_e32 v131, v131
	v_exp_f32_e32 v132, v132
	v_exp_f32_e32 v133, v133
	v_pk_add_f32 v[130:131], v[130:131], v[140:141]
	v_pk_add_f32 v[132:133], v[132:133], v[140:141]
	v_rcp_f32_e32 v130, v130
	v_rcp_f32_e32 v131, v131
	v_rcp_f32_e32 v132, v132
	v_rcp_f32_e32 v133, v133
	v_pk_mul_f32 v[118:119], v[118:119], v[130:131]
	v_pk_mul_f32 v[120:121], v[120:121], v[132:133]
	v_cvt_pk_bf16_f32 v118, v118, v119
	v_cvt_pk_bf16_f32 v119, v120, v121
	ds_write_b64 v138, v[118:119]
	v_pk_mul_f32 v[130:131], v[114:115], v[134:135]
	v_pk_mul_f32 v[132:133], v[116:117], v[134:135]
	v_exp_f32_e32 v130, v130
	v_exp_f32_e32 v131, v131
	v_exp_f32_e32 v132, v132
	v_exp_f32_e32 v133, v133
	v_pk_add_f32 v[130:131], v[130:131], v[140:141]
	v_pk_add_f32 v[132:133], v[132:133], v[140:141]
	v_rcp_f32_e32 v130, v130
	v_rcp_f32_e32 v131, v131
	v_rcp_f32_e32 v132, v132
	v_rcp_f32_e32 v133, v133
	v_pk_mul_f32 v[114:115], v[114:115], v[130:131]
	v_pk_mul_f32 v[116:117], v[116:117], v[132:133]
	v_cvt_pk_bf16_f32 v114, v114, v115
	v_cvt_pk_bf16_f32 v115, v116, v117
	ds_write_b64 v139, v[114:115]
	v_pk_mul_f32 v[130:131], v[110:111], v[134:135]
	v_pk_mul_f32 v[132:133], v[112:113], v[134:135]
	v_exp_f32_e32 v130, v130
	v_exp_f32_e32 v131, v131
	v_exp_f32_e32 v132, v132
	v_exp_f32_e32 v133, v133
	v_pk_add_f32 v[130:131], v[130:131], v[140:141]
	v_pk_add_f32 v[132:133], v[132:133], v[140:141]
	v_rcp_f32_e32 v130, v130
	v_rcp_f32_e32 v131, v131
	v_rcp_f32_e32 v132, v132
	v_rcp_f32_e32 v133, v133
	v_pk_mul_f32 v[110:111], v[110:111], v[130:131]
	v_pk_mul_f32 v[112:113], v[112:113], v[132:133]
	v_cvt_pk_bf16_f32 v110, v110, v111
	v_cvt_pk_bf16_f32 v111, v112, v113
	ds_write_b64 v136, v[110:111] offset:2048
	v_pk_mul_f32 v[130:131], v[106:107], v[134:135]
	v_pk_mul_f32 v[132:133], v[108:109], v[134:135]
	v_exp_f32_e32 v130, v130
	v_exp_f32_e32 v131, v131
	v_exp_f32_e32 v132, v132
	v_exp_f32_e32 v133, v133
	v_pk_add_f32 v[130:131], v[130:131], v[140:141]
	v_pk_add_f32 v[132:133], v[132:133], v[140:141]
	v_rcp_f32_e32 v130, v130
	v_rcp_f32_e32 v131, v131
	v_rcp_f32_e32 v132, v132
	v_rcp_f32_e32 v133, v133
	v_pk_mul_f32 v[106:107], v[106:107], v[130:131]
	v_pk_mul_f32 v[108:109], v[108:109], v[132:133]
	v_cvt_pk_bf16_f32 v106, v106, v107
	v_cvt_pk_bf16_f32 v107, v108, v109
	ds_write_b64 v137, v[106:107] offset:2048
	v_pk_mul_f32 v[130:131], v[102:103], v[134:135]
	v_pk_mul_f32 v[132:133], v[104:105], v[134:135]
	v_exp_f32_e32 v130, v130
	v_exp_f32_e32 v131, v131
	v_exp_f32_e32 v132, v132
	v_exp_f32_e32 v133, v133
	v_pk_add_f32 v[130:131], v[130:131], v[140:141]
	v_pk_add_f32 v[132:133], v[132:133], v[140:141]
	v_rcp_f32_e32 v130, v130
	v_rcp_f32_e32 v131, v131
	v_rcp_f32_e32 v132, v132
	v_rcp_f32_e32 v133, v133
	v_pk_mul_f32 v[102:103], v[102:103], v[130:131]
	v_pk_mul_f32 v[104:105], v[104:105], v[132:133]
	v_cvt_pk_bf16_f32 v102, v102, v103
	v_cvt_pk_bf16_f32 v103, v104, v105
	ds_write_b64 v138, v[102:103] offset:2048
	v_pk_mul_f32 v[130:131], v[98:99], v[134:135]
	v_pk_mul_f32 v[132:133], v[100:101], v[134:135]
	v_exp_f32_e32 v130, v130
	v_exp_f32_e32 v131, v131
	v_exp_f32_e32 v132, v132
	v_exp_f32_e32 v133, v133
	v_pk_add_f32 v[130:131], v[130:131], v[140:141]
	v_pk_add_f32 v[132:133], v[132:133], v[140:141]
	v_rcp_f32_e32 v130, v130
	v_rcp_f32_e32 v131, v131
	v_rcp_f32_e32 v132, v132
	v_rcp_f32_e32 v133, v133
	v_pk_mul_f32 v[98:99], v[98:99], v[130:131]
	v_pk_mul_f32 v[100:101], v[100:101], v[132:133]
	v_cvt_pk_bf16_f32 v98, v98, v99
	v_cvt_pk_bf16_f32 v99, v100, v101
	ds_write_b64 v139, v[98:99] offset:2048
	v_pk_mul_f32 v[130:131], v[94:95], v[134:135]
	v_pk_mul_f32 v[132:133], v[96:97], v[134:135]
	v_exp_f32_e32 v130, v130
	v_exp_f32_e32 v131, v131
	v_exp_f32_e32 v132, v132
	v_exp_f32_e32 v133, v133
	v_pk_add_f32 v[130:131], v[130:131], v[140:141]
	v_pk_add_f32 v[132:133], v[132:133], v[140:141]
	v_rcp_f32_e32 v130, v130
	v_rcp_f32_e32 v131, v131
	v_rcp_f32_e32 v132, v132
	v_rcp_f32_e32 v133, v133
	v_pk_mul_f32 v[94:95], v[94:95], v[130:131]
	v_pk_mul_f32 v[96:97], v[96:97], v[132:133]
	v_cvt_pk_bf16_f32 v94, v94, v95
	v_cvt_pk_bf16_f32 v95, v96, v97
	ds_write_b64 v136, v[94:95] offset:4096
	v_pk_mul_f32 v[130:131], v[90:91], v[134:135]
	v_pk_mul_f32 v[132:133], v[92:93], v[134:135]
	v_exp_f32_e32 v130, v130
	v_exp_f32_e32 v131, v131
; __device__ __forceinline__ float sigmf(float v) { return __builtin_amdgcn_rcpf(1.f + __builtin_amdgcn_exp2f(-1.4426950408889634f * v)); }
; #define G1_STG(mi_, ni_, v_) do { const int r_ = (mi_) * 16 + idx; const f32x4 t_ = (v_); u32x2 pk_; pk_.x = pk2(t_.x, t_.y); pk_.y = pk2(t_.z, t_.w); \
;         *(u32x2*)(wl + r_ * 128 + ((((ni_) * 2 + (kq >> 1)) ^ (r_ & 7)) * 16) + (kq & 1) * 8) = pk_; } while (0)
; __device__ __forceinline__ float siluf(float v) { return v * __builtin_amdgcn_rcpf(1.f + __builtin_amdgcn_exp2f(-1.4426950408889634f * v)); }
; __device__ void gemm1_phase(const Params& p, int l, int hb, unsigned char* smem) {
;     ...
;                 for (int ni = 0; ni < 4; ++ni) {
;                     f32x4 v = acc[mi][ni];
;                     if (mode == 1) { v.x = siluf(v.x); v.y = siluf(v.y); v.z = siluf(v.z); v.w = siluf(v.w); }
;                     else if (mode == 2) { const f32x4 bb = *(const f32x4*)(bg + ni * 16); v.x = sigmf(v.x + bb.x); v.y = sigmf(v.y + bb.y); v.z = sigmf(v.z + bb.z); v.w = sigmf(v.w + bb.w); }
;                     G1_STG(mi, ni, v);
	v_exp_f32_e32 v132, v132
	v_exp_f32_e32 v133, v133
	v_pk_add_f32 v[130:131], v[130:131], v[140:141]
	v_pk_add_f32 v[132:133], v[132:133], v[140:141]
	v_rcp_f32_e32 v130, v130
	v_rcp_f32_e32 v131, v131
	v_rcp_f32_e32 v132, v132
	v_rcp_f32_e32 v133, v133
	v_pk_mul_f32 v[90:91], v[90:91], v[130:131]
	v_pk_mul_f32 v[92:93], v[92:93], v[132:133]
	v_cvt_pk_bf16_f32 v90, v90, v91
	v_cvt_pk_bf16_f32 v91, v92, v93
	ds_write_b64 v137, v[90:91] offset:4096
	v_pk_mul_f32 v[130:131], v[86:87], v[134:135]
	v_pk_mul_f32 v[132:133], v[88:89], v[134:135]
	v_exp_f32_e32 v130, v130
	v_exp_f32_e32 v131, v131
	v_exp_f32_e32 v132, v132
	v_exp_f32_e32 v133, v133
	v_pk_add_f32 v[130:131], v[130:131], v[140:141]
	v_pk_add_f32 v[132:133], v[132:133], v[140:141]
	v_rcp_f32_e32 v130, v130
	v_rcp_f32_e32 v131, v131
	v_rcp_f32_e32 v132, v132
	v_rcp_f32_e32 v133, v133
	v_pk_mul_f32 v[86:87], v[86:87], v[130:131]
	v_pk_mul_f32 v[88:89], v[88:89], v[132:133]
	v_cvt_pk_bf16_f32 v86, v86, v87
	v_cvt_pk_bf16_f32 v87, v88, v89
	ds_write_b64 v138, v[86:87] offset:4096
	v_pk_mul_f32 v[130:131], v[82:83], v[134:135]
	v_pk_mul_f32 v[132:133], v[84:85], v[134:135]
	v_exp_f32_e32 v130, v130
	v_exp_f32_e32 v131, v131
	v_exp_f32_e32 v132, v132
	v_exp_f32_e32 v133, v133
	v_pk_add_f32 v[130:131], v[130:131], v[140:141]
	v_pk_add_f32 v[132:133], v[132:133], v[140:141]
	v_rcp_f32_e32 v130, v130
	v_rcp_f32_e32 v131, v131
	v_rcp_f32_e32 v132, v132
	v_rcp_f32_e32 v133, v133
	v_pk_mul_f32 v[82:83], v[82:83], v[130:131]
	v_pk_mul_f32 v[84:85], v[84:85], v[132:133]
	v_cvt_pk_bf16_f32 v82, v82, v83
	v_cvt_pk_bf16_f32 v83, v84, v85
	ds_write_b64 v139, v[82:83] offset:4096
	v_pk_mul_f32 v[130:131], v[76:77], v[134:135]
	v_pk_mul_f32 v[132:133], v[78:79], v[134:135]
	v_exp_f32_e32 v130, v130
	v_exp_f32_e32 v131, v131
	v_exp_f32_e32 v132, v132
	v_exp_f32_e32 v133, v133
	v_pk_add_f32 v[130:131], v[130:131], v[140:141]
	v_pk_add_f32 v[132:133], v[132:133], v[140:141]
	v_rcp_f32_e32 v130, v130
	v_rcp_f32_e32 v131, v131
	v_rcp_f32_e32 v132, v132
	v_rcp_f32_e32 v133, v133
	v_pk_mul_f32 v[76:77], v[76:77], v[130:131]
	v_pk_mul_f32 v[78:79], v[78:79], v[132:133]
	v_cvt_pk_bf16_f32 v76, v76, v77
	v_cvt_pk_bf16_f32 v77, v78, v79
	ds_write_b64 v136, v[76:77] offset:6144
	v_pk_mul_f32 v[130:131], v[72:73], v[134:135]
	v_pk_mul_f32 v[132:133], v[74:75], v[134:135]
	v_exp_f32_e32 v130, v130
	v_exp_f32_e32 v131, v131
	v_exp_f32_e32 v132, v132
	v_exp_f32_e32 v133, v133
	v_pk_add_f32 v[130:131], v[130:131], v[140:141]
	v_pk_add_f32 v[132:133], v[132:133], v[140:141]
	v_rcp_f32_e32 v130, v130
	v_rcp_f32_e32 v131, v131
	v_rcp_f32_e32 v132, v132
	v_rcp_f32_e32 v133, v133
	v_pk_mul_f32 v[72:73], v[72:73], v[130:131]
	v_pk_mul_f32 v[74:75], v[74:75], v[132:133]
	v_cvt_pk_bf16_f32 v72, v72, v73
	v_cvt_pk_bf16_f32 v73, v74, v75
	ds_write_b64 v137, v[72:73] offset:6144
	v_pk_mul_f32 v[130:131], v[68:69], v[134:135]
	v_pk_mul_f32 v[132:133], v[70:71], v[134:135]
	v_exp_f32_e32 v130, v130
	v_exp_f32_e32 v131, v131
	v_exp_f32_e32 v132, v132
	v_exp_f32_e32 v133, v133
	v_pk_add_f32 v[130:131], v[130:131], v[140:141]
	v_pk_add_f32 v[132:133], v[132:133], v[140:141]
	v_rcp_f32_e32 v130, v130
	v_rcp_f32_e32 v131, v131
	v_rcp_f32_e32 v132, v132
	v_rcp_f32_e32 v133, v133
	v_pk_mul_f32 v[68:69], v[68:69], v[130:131]
	v_pk_mul_f32 v[70:71], v[70:71], v[132:133]
	v_cvt_pk_bf16_f32 v68, v68, v69
	v_cvt_pk_bf16_f32 v69, v70, v71
	ds_write_b64 v138, v[68:69] offset:6144
	v_pk_mul_f32 v[130:131], v[64:65], v[134:135]
	v_pk_mul_f32 v[132:133], v[66:67], v[134:135]
	v_exp_f32_e32 v130, v130
	v_exp_f32_e32 v131, v131
	v_exp_f32_e32 v132, v132
	v_exp_f32_e32 v133, v133
	v_pk_add_f32 v[130:131], v[130:131], v[140:141]
	v_pk_add_f32 v[132:133], v[132:133], v[140:141]
	v_rcp_f32_e32 v130, v130
	v_rcp_f32_e32 v131, v131
	v_rcp_f32_e32 v132, v132
	v_rcp_f32_e32 v133, v133
	v_pk_mul_f32 v[64:65], v[64:65], v[130:131]
	v_pk_mul_f32 v[66:67], v[66:67], v[132:133]
	v_cvt_pk_bf16_f32 v64, v64, v65
	v_cvt_pk_bf16_f32 v65, v66, v67
	ds_write_b64 v139, v[64:65] offset:6144
	v_pk_mul_f32 v[130:131], v[60:61], v[134:135]
	v_pk_mul_f32 v[132:133], v[62:63], v[134:135]
	v_exp_f32_e32 v130, v130
	v_exp_f32_e32 v131, v131
	v_exp_f32_e32 v132, v132
	v_exp_f32_e32 v133, v133
	v_pk_add_f32 v[130:131], v[130:131], v[140:141]
	v_pk_add_f32 v[132:133], v[132:133], v[140:141]
	v_rcp_f32_e32 v130, v130
	v_rcp_f32_e32 v131, v131
	v_rcp_f32_e32 v132, v132
	v_rcp_f32_e32 v133, v133
	v_pk_mul_f32 v[60:61], v[60:61], v[130:131]
	v_pk_mul_f32 v[62:63], v[62:63], v[132:133]
	v_cvt_pk_bf16_f32 v60, v60, v61
	v_cvt_pk_bf16_f32 v61, v62, v63
	ds_write_b64 v136, v[60:61] offset:8192
	v_pk_mul_f32 v[130:131], v[56:57], v[134:135]
	v_pk_mul_f32 v[132:133], v[58:59], v[134:135]
	v_exp_f32_e32 v130, v130
	v_exp_f32_e32 v131, v131
	v_exp_f32_e32 v132, v132
	v_exp_f32_e32 v133, v133
	v_pk_add_f32 v[130:131], v[130:131], v[140:141]
	v_pk_add_f32 v[132:133], v[132:133], v[140:141]
	v_rcp_f32_e32 v130, v130
	v_rcp_f32_e32 v131, v131
	v_rcp_f32_e32 v132, v132
	v_rcp_f32_e32 v133, v133
	v_pk_mul_f32 v[56:57], v[56:57], v[130:131]
	v_pk_mul_f32 v[58:59], v[58:59], v[132:133]
	v_cvt_pk_bf16_f32 v56, v56, v57
	v_cvt_pk_bf16_f32 v57, v58, v59
	ds_write_b64 v137, v[56:57] offset:8192
	v_pk_mul_f32 v[130:131], v[52:53], v[134:135]
	v_pk_mul_f32 v[132:133], v[54:55], v[134:135]
	v_exp_f32_e32 v130, v130
	v_exp_f32_e32 v131, v131
	v_exp_f32_e32 v132, v132
	v_exp_f32_e32 v133, v133
	v_pk_add_f32 v[130:131], v[130:131], v[140:141]
	v_pk_add_f32 v[132:133], v[132:133], v[140:141]
	v_rcp_f32_e32 v130, v130
	v_rcp_f32_e32 v131, v131
	v_rcp_f32_e32 v132, v132
	v_rcp_f32_e32 v133, v133
; __device__ __forceinline__ float sigmf(float v) { return __builtin_amdgcn_rcpf(1.f + __builtin_amdgcn_exp2f(-1.4426950408889634f * v)); }
; #define G1_STG(mi_, ni_, v_) do { const int r_ = (mi_) * 16 + idx; const f32x4 t_ = (v_); u32x2 pk_; pk_.x = pk2(t_.x, t_.y); pk_.y = pk2(t_.z, t_.w); \
;         *(u32x2*)(wl + r_ * 128 + ((((ni_) * 2 + (kq >> 1)) ^ (r_ & 7)) * 16) + (kq & 1) * 8) = pk_; } while (0)
; __device__ __forceinline__ float siluf(float v) { return v * __builtin_amdgcn_rcpf(1.f + __builtin_amdgcn_exp2f(-1.4426950408889634f * v)); }
; __device__ void gemm1_phase(const Params& p, int l, int hb, unsigned char* smem) {
;     ...
;                 for (int ni = 0; ni < 4; ++ni) {
;                     f32x4 v = acc[mi][ni];
;                     if (mode == 1) { v.x = siluf(v.x); v.y = siluf(v.y); v.z = siluf(v.z); v.w = siluf(v.w); }
;                     else if (mode == 2) { const f32x4 bb = *(const f32x4*)(bg + ni * 16); v.x = sigmf(v.x + bb.x); v.y = sigmf(v.y + bb.y); v.z = sigmf(v.z + bb.z); v.w = sigmf(v.w + bb.w); }
;                     G1_STG(mi, ni, v);
	v_pk_mul_f32 v[52:53], v[52:53], v[130:131]
	v_pk_mul_f32 v[54:55], v[54:55], v[132:133]
	v_cvt_pk_bf16_f32 v52, v52, v53
	v_cvt_pk_bf16_f32 v53, v54, v55
	ds_write_b64 v138, v[52:53] offset:8192
	v_pk_mul_f32 v[130:131], v[48:49], v[134:135]
	v_pk_mul_f32 v[132:133], v[50:51], v[134:135]
	v_exp_f32_e32 v130, v130
	v_exp_f32_e32 v131, v131
	v_exp_f32_e32 v132, v132
	v_exp_f32_e32 v133, v133
	v_pk_add_f32 v[130:131], v[130:131], v[140:141]
	v_pk_add_f32 v[132:133], v[132:133], v[140:141]
	v_rcp_f32_e32 v130, v130
	v_rcp_f32_e32 v131, v131
	v_rcp_f32_e32 v132, v132
	v_rcp_f32_e32 v133, v133
	v_pk_mul_f32 v[48:49], v[48:49], v[130:131]
	v_pk_mul_f32 v[50:51], v[50:51], v[132:133]
	v_cvt_pk_bf16_f32 v48, v48, v49
	v_cvt_pk_bf16_f32 v49, v50, v51
	ds_write_b64 v139, v[48:49] offset:8192
	v_pk_mul_f32 v[130:131], v[44:45], v[134:135]
	v_pk_mul_f32 v[132:133], v[46:47], v[134:135]
	v_exp_f32_e32 v130, v130
	v_exp_f32_e32 v131, v131
	v_exp_f32_e32 v132, v132
	v_exp_f32_e32 v133, v133
	v_pk_add_f32 v[130:131], v[130:131], v[140:141]
	v_pk_add_f32 v[132:133], v[132:133], v[140:141]
	v_rcp_f32_e32 v130, v130
	v_rcp_f32_e32 v131, v131
	v_rcp_f32_e32 v132, v132
	v_rcp_f32_e32 v133, v133
	v_pk_mul_f32 v[44:45], v[44:45], v[130:131]
	v_pk_mul_f32 v[46:47], v[46:47], v[132:133]
	v_cvt_pk_bf16_f32 v44, v44, v45
	v_cvt_pk_bf16_f32 v45, v46, v47
	ds_write_b64 v136, v[44:45] offset:10240
	v_pk_mul_f32 v[130:131], v[40:41], v[134:135]
	v_pk_mul_f32 v[132:133], v[42:43], v[134:135]
	v_exp_f32_e32 v130, v130
	v_exp_f32_e32 v131, v131
	v_exp_f32_e32 v132, v132
	v_exp_f32_e32 v133, v133
	v_pk_add_f32 v[130:131], v[130:131], v[140:141]
	v_pk_add_f32 v[132:133], v[132:133], v[140:141]
	v_rcp_f32_e32 v130, v130
	v_rcp_f32_e32 v131, v131
	v_rcp_f32_e32 v132, v132
	v_rcp_f32_e32 v133, v133
	v_pk_mul_f32 v[40:41], v[40:41], v[130:131]
	v_pk_mul_f32 v[42:43], v[42:43], v[132:133]
	v_cvt_pk_bf16_f32 v40, v40, v41
	v_cvt_pk_bf16_f32 v41, v42, v43
	ds_write_b64 v137, v[40:41] offset:10240
	v_pk_mul_f32 v[130:131], v[36:37], v[134:135]
	v_pk_mul_f32 v[132:133], v[38:39], v[134:135]
	v_exp_f32_e32 v130, v130
	v_exp_f32_e32 v131, v131
	v_exp_f32_e32 v132, v132
	v_exp_f32_e32 v133, v133
	v_pk_add_f32 v[130:131], v[130:131], v[140:141]
	v_pk_add_f32 v[132:133], v[132:133], v[140:141]
	v_rcp_f32_e32 v130, v130
	v_rcp_f32_e32 v131, v131
	v_rcp_f32_e32 v132, v132
	v_rcp_f32_e32 v133, v133
	v_pk_mul_f32 v[36:37], v[36:37], v[130:131]
	v_pk_mul_f32 v[38:39], v[38:39], v[132:133]
	v_cvt_pk_bf16_f32 v36, v36, v37
	v_cvt_pk_bf16_f32 v37, v38, v39
	ds_write_b64 v138, v[36:37] offset:10240
	v_pk_mul_f32 v[130:131], v[32:33], v[134:135]
	v_pk_mul_f32 v[132:133], v[34:35], v[134:135]
	v_exp_f32_e32 v130, v130
	v_exp_f32_e32 v131, v131
	v_exp_f32_e32 v132, v132
	v_exp_f32_e32 v133, v133
	v_pk_add_f32 v[130:131], v[130:131], v[140:141]
	v_pk_add_f32 v[132:133], v[132:133], v[140:141]
	v_rcp_f32_e32 v130, v130
	v_rcp_f32_e32 v131, v131
	v_rcp_f32_e32 v132, v132
	v_rcp_f32_e32 v133, v133
	v_pk_mul_f32 v[32:33], v[32:33], v[130:131]
	v_pk_mul_f32 v[34:35], v[34:35], v[132:133]
	v_cvt_pk_bf16_f32 v32, v32, v33
	v_cvt_pk_bf16_f32 v33, v34, v35
	ds_write_b64 v139, v[32:33] offset:10240
	v_pk_mul_f32 v[130:131], v[28:29], v[134:135]
	v_pk_mul_f32 v[132:133], v[30:31], v[134:135]
	v_exp_f32_e32 v130, v130
	v_exp_f32_e32 v131, v131
	v_exp_f32_e32 v132, v132
	v_exp_f32_e32 v133, v133
	v_pk_add_f32 v[130:131], v[130:131], v[140:141]
	v_pk_add_f32 v[132:133], v[132:133], v[140:141]
	v_rcp_f32_e32 v130, v130
	v_rcp_f32_e32 v131, v131
	v_rcp_f32_e32 v132, v132
	v_rcp_f32_e32 v133, v133
	v_pk_mul_f32 v[28:29], v[28:29], v[130:131]
	v_pk_mul_f32 v[30:31], v[30:31], v[132:133]
	v_cvt_pk_bf16_f32 v28, v28, v29
	v_cvt_pk_bf16_f32 v29, v30, v31
	ds_write_b64 v136, v[28:29] offset:12288
	v_pk_mul_f32 v[130:131], v[24:25], v[134:135]
	v_pk_mul_f32 v[132:133], v[26:27], v[134:135]
	v_exp_f32_e32 v130, v130
	v_exp_f32_e32 v131, v131
	v_exp_f32_e32 v132, v132
	v_exp_f32_e32 v133, v133
	v_pk_add_f32 v[130:131], v[130:131], v[140:141]
	v_pk_add_f32 v[132:133], v[132:133], v[140:141]
	v_rcp_f32_e32 v130, v130
	v_rcp_f32_e32 v131, v131
	v_rcp_f32_e32 v132, v132
	v_rcp_f32_e32 v133, v133
	v_pk_mul_f32 v[24:25], v[24:25], v[130:131]
	v_pk_mul_f32 v[26:27], v[26:27], v[132:133]
	v_cvt_pk_bf16_f32 v24, v24, v25
	v_cvt_pk_bf16_f32 v25, v26, v27
	ds_write_b64 v137, v[24:25] offset:12288
	v_pk_mul_f32 v[130:131], v[20:21], v[134:135]
	v_pk_mul_f32 v[132:133], v[22:23], v[134:135]
	v_exp_f32_e32 v130, v130
	v_exp_f32_e32 v131, v131
	v_exp_f32_e32 v132, v132
	v_exp_f32_e32 v133, v133
	v_pk_add_f32 v[130:131], v[130:131], v[140:141]
	v_pk_add_f32 v[132:133], v[132:133], v[140:141]
	v_rcp_f32_e32 v130, v130
	v_rcp_f32_e32 v131, v131
	v_rcp_f32_e32 v132, v132
	v_rcp_f32_e32 v133, v133
	v_pk_mul_f32 v[20:21], v[20:21], v[130:131]
	v_pk_mul_f32 v[22:23], v[22:23], v[132:133]
	v_cvt_pk_bf16_f32 v20, v20, v21
	v_cvt_pk_bf16_f32 v21, v22, v23
	ds_write_b64 v138, v[20:21] offset:12288
	v_pk_mul_f32 v[130:131], v[16:17], v[134:135]
	v_pk_mul_f32 v[132:133], v[18:19], v[134:135]
	v_exp_f32_e32 v130, v130
	v_exp_f32_e32 v131, v131
	v_exp_f32_e32 v132, v132
	v_exp_f32_e32 v133, v133
	v_pk_add_f32 v[130:131], v[130:131], v[140:141]
	v_pk_add_f32 v[132:133], v[132:133], v[140:141]
	v_rcp_f32_e32 v130, v130
	v_rcp_f32_e32 v131, v131
	v_rcp_f32_e32 v132, v132
	v_rcp_f32_e32 v133, v133
	v_pk_mul_f32 v[16:17], v[16:17], v[130:131]
	v_pk_mul_f32 v[18:19], v[18:19], v[132:133]
	v_cvt_pk_bf16_f32 v16, v16, v17
	v_cvt_pk_bf16_f32 v17, v18, v19
	ds_write_b64 v139, v[16:17] offset:12288
	v_pk_mul_f32 v[130:131], v[12:13], v[134:135]
; #define G1_STG(mi_, ni_, v_) do { const int r_ = (mi_) * 16 + idx; const f32x4 t_ = (v_); u32x2 pk_; pk_.x = pk2(t_.x, t_.y); pk_.y = pk2(t_.z, t_.w); \
;         *(u32x2*)(wl + r_ * 128 + ((((ni_) * 2 + (kq >> 1)) ^ (r_ & 7)) * 16) + (kq & 1) * 8) = pk_; } while (0)
; __device__ __forceinline__ float siluf(float v) { return v * __builtin_amdgcn_rcpf(1.f + __builtin_amdgcn_exp2f(-1.4426950408889634f * v)); }
; __device__ __forceinline__ float sigmf(float v) { return __builtin_amdgcn_rcpf(1.f + __builtin_amdgcn_exp2f(-1.4426950408889634f * v)); }
; __device__ void gemm1_phase(const Params& p, int l, int hb, unsigned char* smem) {
;     ...
;                 for (int ni = 0; ni < 4; ++ni) {
;                     f32x4 v = acc[mi][ni];
;                     if (mode == 1) { v.x = siluf(v.x); v.y = siluf(v.y); v.z = siluf(v.z); v.w = siluf(v.w); }
;                     else if (mode == 2) { const f32x4 bb = *(const f32x4*)(bg + ni * 16); v.x = sigmf(v.x + bb.x); v.y = sigmf(v.y + bb.y); v.z = sigmf(v.z + bb.z); v.w = sigmf(v.w + bb.w); }
;                     G1_STG(mi, ni, v);
	v_pk_mul_f32 v[132:133], v[14:15], v[134:135]
	v_exp_f32_e32 v130, v130
	v_exp_f32_e32 v131, v131
	v_exp_f32_e32 v132, v132
	v_exp_f32_e32 v133, v133
	v_pk_add_f32 v[130:131], v[130:131], v[140:141]
	v_pk_add_f32 v[132:133], v[132:133], v[140:141]
	v_rcp_f32_e32 v130, v130
	v_rcp_f32_e32 v131, v131
	v_rcp_f32_e32 v132, v132
	v_rcp_f32_e32 v133, v133
	v_pk_mul_f32 v[12:13], v[12:13], v[130:131]
	v_pk_mul_f32 v[14:15], v[14:15], v[132:133]
	v_cvt_pk_bf16_f32 v12, v12, v13
	v_cvt_pk_bf16_f32 v13, v14, v15
	ds_write_b64 v136, v[12:13] offset:14336
	v_pk_mul_f32 v[130:131], v[8:9], v[134:135]
	v_pk_mul_f32 v[132:133], v[10:11], v[134:135]
	v_exp_f32_e32 v130, v130
	v_exp_f32_e32 v131, v131
	v_exp_f32_e32 v132, v132
	v_exp_f32_e32 v133, v133
	v_pk_add_f32 v[130:131], v[130:131], v[140:141]
	v_pk_add_f32 v[132:133], v[132:133], v[140:141]
	v_rcp_f32_e32 v130, v130
	v_rcp_f32_e32 v131, v131
	v_rcp_f32_e32 v132, v132
	v_rcp_f32_e32 v133, v133
	v_pk_mul_f32 v[8:9], v[8:9], v[130:131]
	v_pk_mul_f32 v[10:11], v[10:11], v[132:133]
	v_cvt_pk_bf16_f32 v8, v8, v9
	v_cvt_pk_bf16_f32 v9, v10, v11
	ds_write_b64 v137, v[8:9] offset:14336
	v_pk_mul_f32 v[130:131], v[4:5], v[134:135]
	v_pk_mul_f32 v[132:133], v[6:7], v[134:135]
	v_exp_f32_e32 v130, v130
	v_exp_f32_e32 v131, v131
	v_exp_f32_e32 v132, v132
	v_exp_f32_e32 v133, v133
	v_pk_add_f32 v[130:131], v[130:131], v[140:141]
	v_pk_add_f32 v[132:133], v[132:133], v[140:141]
	v_rcp_f32_e32 v130, v130
	v_rcp_f32_e32 v131, v131
	v_rcp_f32_e32 v132, v132
	v_rcp_f32_e32 v133, v133
	v_pk_mul_f32 v[4:5], v[4:5], v[130:131]
	v_pk_mul_f32 v[6:7], v[6:7], v[132:133]
	v_cvt_pk_bf16_f32 v4, v4, v5
	v_cvt_pk_bf16_f32 v5, v6, v7
	ds_write_b64 v138, v[4:5] offset:14336
	v_pk_mul_f32 v[130:131], v[0:1], v[134:135]
	v_pk_mul_f32 v[132:133], v[2:3], v[134:135]
	v_exp_f32_e32 v130, v130
	v_exp_f32_e32 v131, v131
	v_exp_f32_e32 v132, v132
	v_exp_f32_e32 v133, v133
	v_pk_add_f32 v[130:131], v[130:131], v[140:141]
	v_pk_add_f32 v[132:133], v[132:133], v[140:141]
	v_rcp_f32_e32 v130, v130
	v_rcp_f32_e32 v131, v131
	v_rcp_f32_e32 v132, v132
	v_rcp_f32_e32 v133, v133
	v_pk_mul_f32 v[0:1], v[0:1], v[130:131]
	v_pk_mul_f32 v[2:3], v[2:3], v[132:133]
	v_cvt_pk_bf16_f32 v0, v0, v1
	v_cvt_pk_bf16_f32 v1, v2, v3
	ds_write_b64 v139, v[0:1] offset:14336
	s_branch .Lg1e_done
.Lg1e_sig:
	s_waitcnt vmcnt(0)
	v_pk_add_f32 v[130:131], v[126:127], v[160:161]
	v_pk_add_f32 v[132:133], v[128:129], v[162:163]
	v_pk_mul_f32 v[130:131], v[130:131], v[134:135]
	v_pk_mul_f32 v[132:133], v[132:133], v[134:135]
	v_exp_f32_e32 v130, v130
	v_exp_f32_e32 v131, v131
	v_exp_f32_e32 v132, v132
	v_exp_f32_e32 v133, v133
	v_pk_add_f32 v[130:131], v[130:131], v[140:141]
	v_pk_add_f32 v[132:133], v[132:133], v[140:141]
	v_rcp_f32_e32 v130, v130
	v_rcp_f32_e32 v131, v131
	v_rcp_f32_e32 v132, v132
	v_rcp_f32_e32 v133, v133
	s_nop 0
	v_cvt_pk_bf16_f32 v126, v130, v131
	v_cvt_pk_bf16_f32 v127, v132, v133
	ds_write_b64 v136, v[126:127]
	v_pk_add_f32 v[130:131], v[122:123], v[164:165]
	v_pk_add_f32 v[132:133], v[124:125], v[166:167]
	v_pk_mul_f32 v[130:131], v[130:131], v[134:135]
	v_pk_mul_f32 v[132:133], v[132:133], v[134:135]
	v_exp_f32_e32 v130, v130
	v_exp_f32_e32 v131, v131
	v_exp_f32_e32 v132, v132
	v_exp_f32_e32 v133, v133
	v_pk_add_f32 v[130:131], v[130:131], v[140:141]
	v_pk_add_f32 v[132:133], v[132:133], v[140:141]
	v_rcp_f32_e32 v130, v130
	v_rcp_f32_e32 v131, v131
	v_rcp_f32_e32 v132, v132
	v_rcp_f32_e32 v133, v133
	s_nop 0
	v_cvt_pk_bf16_f32 v122, v130, v131
	v_cvt_pk_bf16_f32 v123, v132, v133
	ds_write_b64 v137, v[122:123]
	v_pk_add_f32 v[130:131], v[118:119], v[168:169]
	v_pk_add_f32 v[132:133], v[120:121], v[170:171]
	v_pk_mul_f32 v[130:131], v[130:131], v[134:135]
	v_pk_mul_f32 v[132:133], v[132:133], v[134:135]
	v_exp_f32_e32 v130, v130
	v_exp_f32_e32 v131, v131
	v_exp_f32_e32 v132, v132
	v_exp_f32_e32 v133, v133
	v_pk_add_f32 v[130:131], v[130:131], v[140:141]
	v_pk_add_f32 v[132:133], v[132:133], v[140:141]
	v_rcp_f32_e32 v130, v130
	v_rcp_f32_e32 v131, v131
	v_rcp_f32_e32 v132, v132
	v_rcp_f32_e32 v133, v133
	s_nop 0
	v_cvt_pk_bf16_f32 v118, v130, v131
	v_cvt_pk_bf16_f32 v119, v132, v133
	ds_write_b64 v138, v[118:119]
	v_pk_add_f32 v[130:131], v[114:115], v[172:173]
	v_pk_add_f32 v[132:133], v[116:117], v[174:175]
	v_pk_mul_f32 v[130:131], v[130:131], v[134:135]
	v_pk_mul_f32 v[132:133], v[132:133], v[134:135]
	v_exp_f32_e32 v130, v130
	v_exp_f32_e32 v131, v131
	v_exp_f32_e32 v132, v132
	v_exp_f32_e32 v133, v133
	v_pk_add_f32 v[130:131], v[130:131], v[140:141]
	v_pk_add_f32 v[132:133], v[132:133], v[140:141]
	v_rcp_f32_e32 v130, v130
	v_rcp_f32_e32 v131, v131
	v_rcp_f32_e32 v132, v132
	v_rcp_f32_e32 v133, v133
	s_nop 0
	v_cvt_pk_bf16_f32 v114, v130, v131
	v_cvt_pk_bf16_f32 v115, v132, v133
	ds_write_b64 v139, v[114:115]
	v_pk_add_f32 v[130:131], v[110:111], v[160:161]
	v_pk_add_f32 v[132:133], v[112:113], v[162:163]
	v_pk_mul_f32 v[130:131], v[130:131], v[134:135]
	v_pk_mul_f32 v[132:133], v[132:133], v[134:135]
	v_exp_f32_e32 v130, v130
	v_exp_f32_e32 v131, v131
	v_exp_f32_e32 v132, v132
	v_exp_f32_e32 v133, v133
	v_pk_add_f32 v[130:131], v[130:131], v[140:141]
	v_pk_add_f32 v[132:133], v[132:133], v[140:141]
	v_rcp_f32_e32 v130, v130
	v_rcp_f32_e32 v131, v131
	v_rcp_f32_e32 v132, v132
	v_rcp_f32_e32 v133, v133
	s_nop 0
	v_cvt_pk_bf16_f32 v110, v130, v131
	v_cvt_pk_bf16_f32 v111, v132, v133
	ds_write_b64 v136, v[110:111] offset:2048
	v_pk_add_f32 v[130:131], v[106:107], v[164:165]
	v_pk_add_f32 v[132:133], v[108:109], v[166:167]
	v_pk_mul_f32 v[130:131], v[130:131], v[134:135]
	v_pk_mul_f32 v[132:133], v[132:133], v[134:135]
	v_exp_f32_e32 v130, v130
; #define G1_STG(mi_, ni_, v_) do { const int r_ = (mi_) * 16 + idx; const f32x4 t_ = (v_); u32x2 pk_; pk_.x = pk2(t_.x, t_.y); pk_.y = pk2(t_.z, t_.w); \
;         *(u32x2*)(wl + r_ * 128 + ((((ni_) * 2 + (kq >> 1)) ^ (r_ & 7)) * 16) + (kq & 1) * 8) = pk_; } while (0)
; __device__ __forceinline__ float sigmf(float v) { return __builtin_amdgcn_rcpf(1.f + __builtin_amdgcn_exp2f(-1.4426950408889634f * v)); }
; __device__ void gemm1_phase(const Params& p, int l, int hb, unsigned char* smem) {
;     ...
;                     else if (mode == 2) { const f32x4 bb = *(const f32x4*)(bg + ni * 16); v.x = sigmf(v.x + bb.x); v.y = sigmf(v.y + bb.y); v.z = sigmf(v.z + bb.z); v.w = sigmf(v.w + bb.w); }
;                     G1_STG(mi, ni, v);
	v_exp_f32_e32 v131, v131
	v_exp_f32_e32 v132, v132
	v_exp_f32_e32 v133, v133
	v_pk_add_f32 v[130:131], v[130:131], v[140:141]
	v_pk_add_f32 v[132:133], v[132:133], v[140:141]
	v_rcp_f32_e32 v130, v130
	v_rcp_f32_e32 v131, v131
	v_rcp_f32_e32 v132, v132
	v_rcp_f32_e32 v133, v133
	s_nop 0
	v_cvt_pk_bf16_f32 v106, v130, v131
	v_cvt_pk_bf16_f32 v107, v132, v133
	ds_write_b64 v137, v[106:107] offset:2048
	v_pk_add_f32 v[130:131], v[102:103], v[168:169]
	v_pk_add_f32 v[132:133], v[104:105], v[170:171]
	v_pk_mul_f32 v[130:131], v[130:131], v[134:135]
	v_pk_mul_f32 v[132:133], v[132:133], v[134:135]
	v_exp_f32_e32 v130, v130
	v_exp_f32_e32 v131, v131
	v_exp_f32_e32 v132, v132
	v_exp_f32_e32 v133, v133
	v_pk_add_f32 v[130:131], v[130:131], v[140:141]
	v_pk_add_f32 v[132:133], v[132:133], v[140:141]
	v_rcp_f32_e32 v130, v130
	v_rcp_f32_e32 v131, v131
	v_rcp_f32_e32 v132, v132
	v_rcp_f32_e32 v133, v133
	s_nop 0
	v_cvt_pk_bf16_f32 v102, v130, v131
	v_cvt_pk_bf16_f32 v103, v132, v133
	ds_write_b64 v138, v[102:103] offset:2048
	v_pk_add_f32 v[130:131], v[98:99], v[172:173]
	v_pk_add_f32 v[132:133], v[100:101], v[174:175]
	v_pk_mul_f32 v[130:131], v[130:131], v[134:135]
	v_pk_mul_f32 v[132:133], v[132:133], v[134:135]
	v_exp_f32_e32 v130, v130
	v_exp_f32_e32 v131, v131
	v_exp_f32_e32 v132, v132
	v_exp_f32_e32 v133, v133
	v_pk_add_f32 v[130:131], v[130:131], v[140:141]
	v_pk_add_f32 v[132:133], v[132:133], v[140:141]
	v_rcp_f32_e32 v130, v130
	v_rcp_f32_e32 v131, v131
	v_rcp_f32_e32 v132, v132
	v_rcp_f32_e32 v133, v133
	s_nop 0
	v_cvt_pk_bf16_f32 v98, v130, v131
	v_cvt_pk_bf16_f32 v99, v132, v133
	ds_write_b64 v139, v[98:99] offset:2048
	v_pk_add_f32 v[130:131], v[94:95], v[160:161]
	v_pk_add_f32 v[132:133], v[96:97], v[162:163]
	v_pk_mul_f32 v[130:131], v[130:131], v[134:135]
	v_pk_mul_f32 v[132:133], v[132:133], v[134:135]
	v_exp_f32_e32 v130, v130
	v_exp_f32_e32 v131, v131
	v_exp_f32_e32 v132, v132
	v_exp_f32_e32 v133, v133
	v_pk_add_f32 v[130:131], v[130:131], v[140:141]
	v_pk_add_f32 v[132:133], v[132:133], v[140:141]
	v_rcp_f32_e32 v130, v130
	v_rcp_f32_e32 v131, v131
	v_rcp_f32_e32 v132, v132
	v_rcp_f32_e32 v133, v133
	s_nop 0
	v_cvt_pk_bf16_f32 v94, v130, v131
	v_cvt_pk_bf16_f32 v95, v132, v133
	ds_write_b64 v136, v[94:95] offset:4096
	v_pk_add_f32 v[130:131], v[90:91], v[164:165]
	v_pk_add_f32 v[132:133], v[92:93], v[166:167]
	v_pk_mul_f32 v[130:131], v[130:131], v[134:135]
	v_pk_mul_f32 v[132:133], v[132:133], v[134:135]
	v_exp_f32_e32 v130, v130
	v_exp_f32_e32 v131, v131
	v_exp_f32_e32 v132, v132
	v_exp_f32_e32 v133, v133
	v_pk_add_f32 v[130:131], v[130:131], v[140:141]
	v_pk_add_f32 v[132:133], v[132:133], v[140:141]
	v_rcp_f32_e32 v130, v130
	v_rcp_f32_e32 v131, v131
	v_rcp_f32_e32 v132, v132
	v_rcp_f32_e32 v133, v133
	s_nop 0
	v_cvt_pk_bf16_f32 v90, v130, v131
	v_cvt_pk_bf16_f32 v91, v132, v133
	ds_write_b64 v137, v[90:91] offset:4096
	v_pk_add_f32 v[130:131], v[86:87], v[168:169]
	v_pk_add_f32 v[132:133], v[88:89], v[170:171]
	v_pk_mul_f32 v[130:131], v[130:131], v[134:135]
	v_pk_mul_f32 v[132:133], v[132:133], v[134:135]
	v_exp_f32_e32 v130, v130
	v_exp_f32_e32 v131, v131
	v_exp_f32_e32 v132, v132
	v_exp_f32_e32 v133, v133
	v_pk_add_f32 v[130:131], v[130:131], v[140:141]
	v_pk_add_f32 v[132:133], v[132:133], v[140:141]
	v_rcp_f32_e32 v130, v130
	v_rcp_f32_e32 v131, v131
	v_rcp_f32_e32 v132, v132
	v_rcp_f32_e32 v133, v133
	s_nop 0
	v_cvt_pk_bf16_f32 v86, v130, v131
	v_cvt_pk_bf16_f32 v87, v132, v133
	ds_write_b64 v138, v[86:87] offset:4096
	v_pk_add_f32 v[130:131], v[82:83], v[172:173]
	v_pk_add_f32 v[132:133], v[84:85], v[174:175]
	v_pk_mul_f32 v[130:131], v[130:131], v[134:135]
	v_pk_mul_f32 v[132:133], v[132:133], v[134:135]
	v_exp_f32_e32 v130, v130
	v_exp_f32_e32 v131, v131
	v_exp_f32_e32 v132, v132
	v_exp_f32_e32 v133, v133
	v_pk_add_f32 v[130:131], v[130:131], v[140:141]
	v_pk_add_f32 v[132:133], v[132:133], v[140:141]
	v_rcp_f32_e32 v130, v130
	v_rcp_f32_e32 v131, v131
	v_rcp_f32_e32 v132, v132
	v_rcp_f32_e32 v133, v133
	s_nop 0
	v_cvt_pk_bf16_f32 v82, v130, v131
	v_cvt_pk_bf16_f32 v83, v132, v133
	ds_write_b64 v139, v[82:83] offset:4096
	v_pk_add_f32 v[130:131], v[76:77], v[160:161]
	v_pk_add_f32 v[132:133], v[78:79], v[162:163]
	v_pk_mul_f32 v[130:131], v[130:131], v[134:135]
	v_pk_mul_f32 v[132:133], v[132:133], v[134:135]
	v_exp_f32_e32 v130, v130
	v_exp_f32_e32 v131, v131
	v_exp_f32_e32 v132, v132
	v_exp_f32_e32 v133, v133
	v_pk_add_f32 v[130:131], v[130:131], v[140:141]
	v_pk_add_f32 v[132:133], v[132:133], v[140:141]
	v_rcp_f32_e32 v130, v130
	v_rcp_f32_e32 v131, v131
	v_rcp_f32_e32 v132, v132
	v_rcp_f32_e32 v133, v133
	s_nop 0
	v_cvt_pk_bf16_f32 v76, v130, v131
	v_cvt_pk_bf16_f32 v77, v132, v133
	ds_write_b64 v136, v[76:77] offset:6144
	v_pk_add_f32 v[130:131], v[72:73], v[164:165]
	v_pk_add_f32 v[132:133], v[74:75], v[166:167]
	v_pk_mul_f32 v[130:131], v[130:131], v[134:135]
	v_pk_mul_f32 v[132:133], v[132:133], v[134:135]
	v_exp_f32_e32 v130, v130
	v_exp_f32_e32 v131, v131
	v_exp_f32_e32 v132, v132
	v_exp_f32_e32 v133, v133
	v_pk_add_f32 v[130:131], v[130:131], v[140:141]
	v_pk_add_f32 v[132:133], v[132:133], v[140:141]
	v_rcp_f32_e32 v130, v130
	v_rcp_f32_e32 v131, v131
	v_rcp_f32_e32 v132, v132
	v_rcp_f32_e32 v133, v133
	s_nop 0
	v_cvt_pk_bf16_f32 v72, v130, v131
	v_cvt_pk_bf16_f32 v73, v132, v133
	ds_write_b64 v137, v[72:73] offset:6144
	v_pk_add_f32 v[130:131], v[68:69], v[168:169]
	v_pk_add_f32 v[132:133], v[70:71], v[170:171]
	v_pk_mul_f32 v[130:131], v[130:131], v[134:135]
	v_pk_mul_f32 v[132:133], v[132:133], v[134:135]
	v_exp_f32_e32 v130, v130
	v_exp_f32_e32 v131, v131
	v_exp_f32_e32 v132, v132
; #define G1_STG(mi_, ni_, v_) do { const int r_ = (mi_) * 16 + idx; const f32x4 t_ = (v_); u32x2 pk_; pk_.x = pk2(t_.x, t_.y); pk_.y = pk2(t_.z, t_.w); \
;         *(u32x2*)(wl + r_ * 128 + ((((ni_) * 2 + (kq >> 1)) ^ (r_ & 7)) * 16) + (kq & 1) * 8) = pk_; } while (0)
; __device__ __forceinline__ float sigmf(float v) { return __builtin_amdgcn_rcpf(1.f + __builtin_amdgcn_exp2f(-1.4426950408889634f * v)); }
; __device__ void gemm1_phase(const Params& p, int l, int hb, unsigned char* smem) {
;     ...
;                     else if (mode == 2) { const f32x4 bb = *(const f32x4*)(bg + ni * 16); v.x = sigmf(v.x + bb.x); v.y = sigmf(v.y + bb.y); v.z = sigmf(v.z + bb.z); v.w = sigmf(v.w + bb.w); }
;                     G1_STG(mi, ni, v);
	v_exp_f32_e32 v133, v133
	v_pk_add_f32 v[130:131], v[130:131], v[140:141]
	v_pk_add_f32 v[132:133], v[132:133], v[140:141]
	v_rcp_f32_e32 v130, v130
	v_rcp_f32_e32 v131, v131
	v_rcp_f32_e32 v132, v132
	v_rcp_f32_e32 v133, v133
	s_nop 0
	v_cvt_pk_bf16_f32 v68, v130, v131
	v_cvt_pk_bf16_f32 v69, v132, v133
	ds_write_b64 v138, v[68:69] offset:6144
	v_pk_add_f32 v[130:131], v[64:65], v[172:173]
	v_pk_add_f32 v[132:133], v[66:67], v[174:175]
	v_pk_mul_f32 v[130:131], v[130:131], v[134:135]
	v_pk_mul_f32 v[132:133], v[132:133], v[134:135]
	v_exp_f32_e32 v130, v130
	v_exp_f32_e32 v131, v131
	v_exp_f32_e32 v132, v132
	v_exp_f32_e32 v133, v133
	v_pk_add_f32 v[130:131], v[130:131], v[140:141]
	v_pk_add_f32 v[132:133], v[132:133], v[140:141]
	v_rcp_f32_e32 v130, v130
	v_rcp_f32_e32 v131, v131
	v_rcp_f32_e32 v132, v132
	v_rcp_f32_e32 v133, v133
	s_nop 0
	v_cvt_pk_bf16_f32 v64, v130, v131
	v_cvt_pk_bf16_f32 v65, v132, v133
	ds_write_b64 v139, v[64:65] offset:6144
	v_pk_add_f32 v[130:131], v[60:61], v[160:161]
	v_pk_add_f32 v[132:133], v[62:63], v[162:163]
	v_pk_mul_f32 v[130:131], v[130:131], v[134:135]
	v_pk_mul_f32 v[132:133], v[132:133], v[134:135]
	v_exp_f32_e32 v130, v130
	v_exp_f32_e32 v131, v131
	v_exp_f32_e32 v132, v132
	v_exp_f32_e32 v133, v133
	v_pk_add_f32 v[130:131], v[130:131], v[140:141]
	v_pk_add_f32 v[132:133], v[132:133], v[140:141]
	v_rcp_f32_e32 v130, v130
	v_rcp_f32_e32 v131, v131
	v_rcp_f32_e32 v132, v132
	v_rcp_f32_e32 v133, v133
	s_nop 0
	v_cvt_pk_bf16_f32 v60, v130, v131
	v_cvt_pk_bf16_f32 v61, v132, v133
	ds_write_b64 v136, v[60:61] offset:8192
	v_pk_add_f32 v[130:131], v[56:57], v[164:165]
	v_pk_add_f32 v[132:133], v[58:59], v[166:167]
	v_pk_mul_f32 v[130:131], v[130:131], v[134:135]
	v_pk_mul_f32 v[132:133], v[132:133], v[134:135]
	v_exp_f32_e32 v130, v130
	v_exp_f32_e32 v131, v131
	v_exp_f32_e32 v132, v132
	v_exp_f32_e32 v133, v133
	v_pk_add_f32 v[130:131], v[130:131], v[140:141]
	v_pk_add_f32 v[132:133], v[132:133], v[140:141]
	v_rcp_f32_e32 v130, v130
	v_rcp_f32_e32 v131, v131
	v_rcp_f32_e32 v132, v132
	v_rcp_f32_e32 v133, v133
	s_nop 0
	v_cvt_pk_bf16_f32 v56, v130, v131
	v_cvt_pk_bf16_f32 v57, v132, v133
	ds_write_b64 v137, v[56:57] offset:8192
	v_pk_add_f32 v[130:131], v[52:53], v[168:169]
	v_pk_add_f32 v[132:133], v[54:55], v[170:171]
	v_pk_mul_f32 v[130:131], v[130:131], v[134:135]
	v_pk_mul_f32 v[132:133], v[132:133], v[134:135]
	v_exp_f32_e32 v130, v130
	v_exp_f32_e32 v131, v131
	v_exp_f32_e32 v132, v132
	v_exp_f32_e32 v133, v133
	v_pk_add_f32 v[130:131], v[130:131], v[140:141]
	v_pk_add_f32 v[132:133], v[132:133], v[140:141]
	v_rcp_f32_e32 v130, v130
	v_rcp_f32_e32 v131, v131
	v_rcp_f32_e32 v132, v132
	v_rcp_f32_e32 v133, v133
	s_nop 0
	v_cvt_pk_bf16_f32 v52, v130, v131
	v_cvt_pk_bf16_f32 v53, v132, v133
	ds_write_b64 v138, v[52:53] offset:8192
	v_pk_add_f32 v[130:131], v[48:49], v[172:173]
	v_pk_add_f32 v[132:133], v[50:51], v[174:175]
	v_pk_mul_f32 v[130:131], v[130:131], v[134:135]
	v_pk_mul_f32 v[132:133], v[132:133], v[134:135]
	v_exp_f32_e32 v130, v130
	v_exp_f32_e32 v131, v131
	v_exp_f32_e32 v132, v132
	v_exp_f32_e32 v133, v133
	v_pk_add_f32 v[130:131], v[130:131], v[140:141]
	v_pk_add_f32 v[132:133], v[132:133], v[140:141]
	v_rcp_f32_e32 v130, v130
	v_rcp_f32_e32 v131, v131
	v_rcp_f32_e32 v132, v132
	v_rcp_f32_e32 v133, v133
	s_nop 0
	v_cvt_pk_bf16_f32 v48, v130, v131
	v_cvt_pk_bf16_f32 v49, v132, v133
	ds_write_b64 v139, v[48:49] offset:8192
	v_pk_add_f32 v[130:131], v[44:45], v[160:161]
	v_pk_add_f32 v[132:133], v[46:47], v[162:163]
	v_pk_mul_f32 v[130:131], v[130:131], v[134:135]
	v_pk_mul_f32 v[132:133], v[132:133], v[134:135]
	v_exp_f32_e32 v130, v130
	v_exp_f32_e32 v131, v131
	v_exp_f32_e32 v132, v132
	v_exp_f32_e32 v133, v133
	v_pk_add_f32 v[130:131], v[130:131], v[140:141]
	v_pk_add_f32 v[132:133], v[132:133], v[140:141]
	v_rcp_f32_e32 v130, v130
	v_rcp_f32_e32 v131, v131
	v_rcp_f32_e32 v132, v132
	v_rcp_f32_e32 v133, v133
	s_nop 0
	v_cvt_pk_bf16_f32 v44, v130, v131
	v_cvt_pk_bf16_f32 v45, v132, v133
	ds_write_b64 v136, v[44:45] offset:10240
	v_pk_add_f32 v[130:131], v[40:41], v[164:165]
	v_pk_add_f32 v[132:133], v[42:43], v[166:167]
	v_pk_mul_f32 v[130:131], v[130:131], v[134:135]
	v_pk_mul_f32 v[132:133], v[132:133], v[134:135]
	v_exp_f32_e32 v130, v130
	v_exp_f32_e32 v131, v131
	v_exp_f32_e32 v132, v132
	v_exp_f32_e32 v133, v133
	v_pk_add_f32 v[130:131], v[130:131], v[140:141]
	v_pk_add_f32 v[132:133], v[132:133], v[140:141]
	v_rcp_f32_e32 v130, v130
	v_rcp_f32_e32 v131, v131
	v_rcp_f32_e32 v132, v132
	v_rcp_f32_e32 v133, v133
	s_nop 0
	v_cvt_pk_bf16_f32 v40, v130, v131
	v_cvt_pk_bf16_f32 v41, v132, v133
	ds_write_b64 v137, v[40:41] offset:10240
	v_pk_add_f32 v[130:131], v[36:37], v[168:169]
	v_pk_add_f32 v[132:133], v[38:39], v[170:171]
	v_pk_mul_f32 v[130:131], v[130:131], v[134:135]
	v_pk_mul_f32 v[132:133], v[132:133], v[134:135]
	v_exp_f32_e32 v130, v130
	v_exp_f32_e32 v131, v131
	v_exp_f32_e32 v132, v132
	v_exp_f32_e32 v133, v133
	v_pk_add_f32 v[130:131], v[130:131], v[140:141]
	v_pk_add_f32 v[132:133], v[132:133], v[140:141]
	v_rcp_f32_e32 v130, v130
	v_rcp_f32_e32 v131, v131
	v_rcp_f32_e32 v132, v132
	v_rcp_f32_e32 v133, v133
	s_nop 0
	v_cvt_pk_bf16_f32 v36, v130, v131
	v_cvt_pk_bf16_f32 v37, v132, v133
	ds_write_b64 v138, v[36:37] offset:10240
	v_pk_add_f32 v[130:131], v[32:33], v[172:173]
	v_pk_add_f32 v[132:133], v[34:35], v[174:175]
	v_pk_mul_f32 v[130:131], v[130:131], v[134:135]
; #define G1_STG(mi_, ni_, v_) do { const int r_ = (mi_) * 16 + idx; const f32x4 t_ = (v_); u32x2 pk_; pk_.x = pk2(t_.x, t_.y); pk_.y = pk2(t_.z, t_.w); \
;         *(u32x2*)(wl + r_ * 128 + ((((ni_) * 2 + (kq >> 1)) ^ (r_ & 7)) * 16) + (kq & 1) * 8) = pk_; } while (0)
; __device__ __forceinline__ float sigmf(float v) { return __builtin_amdgcn_rcpf(1.f + __builtin_amdgcn_exp2f(-1.4426950408889634f * v)); }
; __device__ void gemm1_phase(const Params& p, int l, int hb, unsigned char* smem) {
;     ...
;                     else if (mode == 2) { const f32x4 bb = *(const f32x4*)(bg + ni * 16); v.x = sigmf(v.x + bb.x); v.y = sigmf(v.y + bb.y); v.z = sigmf(v.z + bb.z); v.w = sigmf(v.w + bb.w); }
;                     G1_STG(mi, ni, v);
	v_pk_mul_f32 v[132:133], v[132:133], v[134:135]
	v_exp_f32_e32 v130, v130
	v_exp_f32_e32 v131, v131
	v_exp_f32_e32 v132, v132
	v_exp_f32_e32 v133, v133
	v_pk_add_f32 v[130:131], v[130:131], v[140:141]
	v_pk_add_f32 v[132:133], v[132:133], v[140:141]
	v_rcp_f32_e32 v130, v130
	v_rcp_f32_e32 v131, v131
	v_rcp_f32_e32 v132, v132
	v_rcp_f32_e32 v133, v133
	s_nop 0
	v_cvt_pk_bf16_f32 v32, v130, v131
	v_cvt_pk_bf16_f32 v33, v132, v133
	ds_write_b64 v139, v[32:33] offset:10240
	v_pk_add_f32 v[130:131], v[28:29], v[160:161]
	v_pk_add_f32 v[132:133], v[30:31], v[162:163]
	v_pk_mul_f32 v[130:131], v[130:131], v[134:135]
	v_pk_mul_f32 v[132:133], v[132:133], v[134:135]
	v_exp_f32_e32 v130, v130
	v_exp_f32_e32 v131, v131
	v_exp_f32_e32 v132, v132
	v_exp_f32_e32 v133, v133
	v_pk_add_f32 v[130:131], v[130:131], v[140:141]
	v_pk_add_f32 v[132:133], v[132:133], v[140:141]
	v_rcp_f32_e32 v130, v130
	v_rcp_f32_e32 v131, v131
	v_rcp_f32_e32 v132, v132
	v_rcp_f32_e32 v133, v133
	s_nop 0
	v_cvt_pk_bf16_f32 v28, v130, v131
	v_cvt_pk_bf16_f32 v29, v132, v133
	ds_write_b64 v136, v[28:29] offset:12288
	v_pk_add_f32 v[130:131], v[24:25], v[164:165]
	v_pk_add_f32 v[132:133], v[26:27], v[166:167]
	v_pk_mul_f32 v[130:131], v[130:131], v[134:135]
	v_pk_mul_f32 v[132:133], v[132:133], v[134:135]
	v_exp_f32_e32 v130, v130
	v_exp_f32_e32 v131, v131
	v_exp_f32_e32 v132, v132
	v_exp_f32_e32 v133, v133
	v_pk_add_f32 v[130:131], v[130:131], v[140:141]
	v_pk_add_f32 v[132:133], v[132:133], v[140:141]
	v_rcp_f32_e32 v130, v130
	v_rcp_f32_e32 v131, v131
	v_rcp_f32_e32 v132, v132
	v_rcp_f32_e32 v133, v133
	s_nop 0
	v_cvt_pk_bf16_f32 v24, v130, v131
	v_cvt_pk_bf16_f32 v25, v132, v133
	ds_write_b64 v137, v[24:25] offset:12288
	v_pk_add_f32 v[130:131], v[20:21], v[168:169]
	v_pk_add_f32 v[132:133], v[22:23], v[170:171]
	v_pk_mul_f32 v[130:131], v[130:131], v[134:135]
	v_pk_mul_f32 v[132:133], v[132:133], v[134:135]
	v_exp_f32_e32 v130, v130
	v_exp_f32_e32 v131, v131
	v_exp_f32_e32 v132, v132
	v_exp_f32_e32 v133, v133
	v_pk_add_f32 v[130:131], v[130:131], v[140:141]
	v_pk_add_f32 v[132:133], v[132:133], v[140:141]
	v_rcp_f32_e32 v130, v130
	v_rcp_f32_e32 v131, v131
	v_rcp_f32_e32 v132, v132
	v_rcp_f32_e32 v133, v133
	s_nop 0
	v_cvt_pk_bf16_f32 v20, v130, v131
	v_cvt_pk_bf16_f32 v21, v132, v133
	ds_write_b64 v138, v[20:21] offset:12288
	v_pk_add_f32 v[130:131], v[16:17], v[172:173]
	v_pk_add_f32 v[132:133], v[18:19], v[174:175]
	v_pk_mul_f32 v[130:131], v[130:131], v[134:135]
	v_pk_mul_f32 v[132:133], v[132:133], v[134:135]
	v_exp_f32_e32 v130, v130
	v_exp_f32_e32 v131, v131
	v_exp_f32_e32 v132, v132
	v_exp_f32_e32 v133, v133
	v_pk_add_f32 v[130:131], v[130:131], v[140:141]
	v_pk_add_f32 v[132:133], v[132:133], v[140:141]
	v_rcp_f32_e32 v130, v130
	v_rcp_f32_e32 v131, v131
	v_rcp_f32_e32 v132, v132
	v_rcp_f32_e32 v133, v133
	s_nop 0
	v_cvt_pk_bf16_f32 v16, v130, v131
	v_cvt_pk_bf16_f32 v17, v132, v133
	ds_write_b64 v139, v[16:17] offset:12288
	v_pk_add_f32 v[130:131], v[12:13], v[160:161]
	v_pk_add_f32 v[132:133], v[14:15], v[162:163]
	v_pk_mul_f32 v[130:131], v[130:131], v[134:135]
	v_pk_mul_f32 v[132:133], v[132:133], v[134:135]
	v_exp_f32_e32 v130, v130
	v_exp_f32_e32 v131, v131
	v_exp_f32_e32 v132, v132
	v_exp_f32_e32 v133, v133
	v_pk_add_f32 v[130:131], v[130:131], v[140:141]
	v_pk_add_f32 v[132:133], v[132:133], v[140:141]
	v_rcp_f32_e32 v130, v130
	v_rcp_f32_e32 v131, v131
	v_rcp_f32_e32 v132, v132
	v_rcp_f32_e32 v133, v133
	s_nop 0
	v_cvt_pk_bf16_f32 v12, v130, v131
	v_cvt_pk_bf16_f32 v13, v132, v133
	ds_write_b64 v136, v[12:13] offset:14336
	v_pk_add_f32 v[130:131], v[8:9], v[164:165]
	v_pk_add_f32 v[132:133], v[10:11], v[166:167]
	v_pk_mul_f32 v[130:131], v[130:131], v[134:135]
	v_pk_mul_f32 v[132:133], v[132:133], v[134:135]
	v_exp_f32_e32 v130, v130
	v_exp_f32_e32 v131, v131
	v_exp_f32_e32 v132, v132
	v_exp_f32_e32 v133, v133
	v_pk_add_f32 v[130:131], v[130:131], v[140:141]
	v_pk_add_f32 v[132:133], v[132:133], v[140:141]
	v_rcp_f32_e32 v130, v130
	v_rcp_f32_e32 v131, v131
	v_rcp_f32_e32 v132, v132
	v_rcp_f32_e32 v133, v133
	s_nop 0
	v_cvt_pk_bf16_f32 v8, v130, v131
	v_cvt_pk_bf16_f32 v9, v132, v133
	ds_write_b64 v137, v[8:9] offset:14336
	v_pk_add_f32 v[130:131], v[4:5], v[168:169]
	v_pk_add_f32 v[132:133], v[6:7], v[170:171]
	v_pk_mul_f32 v[130:131], v[130:131], v[134:135]
	v_pk_mul_f32 v[132:133], v[132:133], v[134:135]
	v_exp_f32_e32 v130, v130
	v_exp_f32_e32 v131, v131
	v_exp_f32_e32 v132, v132
	v_exp_f32_e32 v133, v133
	v_pk_add_f32 v[130:131], v[130:131], v[140:141]
	v_pk_add_f32 v[132:133], v[132:133], v[140:141]
	v_rcp_f32_e32 v130, v130
	v_rcp_f32_e32 v131, v131
	v_rcp_f32_e32 v132, v132
	v_rcp_f32_e32 v133, v133
	s_nop 0
	v_cvt_pk_bf16_f32 v4, v130, v131
	v_cvt_pk_bf16_f32 v5, v132, v133
	ds_write_b64 v138, v[4:5] offset:14336
	v_pk_add_f32 v[130:131], v[0:1], v[172:173]
	v_pk_add_f32 v[132:133], v[2:3], v[174:175]
	v_pk_mul_f32 v[130:131], v[130:131], v[134:135]
	v_pk_mul_f32 v[132:133], v[132:133], v[134:135]
	v_exp_f32_e32 v130, v130
	v_exp_f32_e32 v131, v131
	v_exp_f32_e32 v132, v132
	v_exp_f32_e32 v133, v133
	v_pk_add_f32 v[130:131], v[130:131], v[140:141]
	v_pk_add_f32 v[132:133], v[132:133], v[140:141]
	v_rcp_f32_e32 v130, v130
	v_rcp_f32_e32 v131, v131
	v_rcp_f32_e32 v132, v132
	v_rcp_f32_e32 v133, v133
	s_nop 0
	v_cvt_pk_bf16_f32 v0, v130, v131
	v_cvt_pk_bf16_f32 v1, v132, v133
	ds_write_b64 v139, v[0:1] offset:14336
